# MLA loop heads aligned to 64 bytes (p2align) + rope-table copy batched
# speedup vs baseline: 1.0115x; 1.0115x over previous
.LBB0_619:
	v_readfirstlane_b32 s12, v170
	s_lshr_b32 s12, s12, 6
	s_mul_i32 s12, s12, 12288
	s_add_i32 s12, s12, 45056
	v_and_b32_e32 v172, 63, v170
	v_lshl_add_u32 v172, v172, 2, s12
	ds_write_b32 v172, v202 offset:0
	ds_write_b32 v172, v203 offset:256
	ds_write_b32 v172, v204 offset:512
	ds_write_b32 v172, v205 offset:768
	ds_write_b32 v172, v206 offset:1024
	ds_write_b32 v172, v207 offset:1280
	ds_write_b32 v172, v208 offset:1536
	ds_write_b32 v172, v209 offset:1792
	ds_write_b32 v172, v210 offset:2048
	ds_write_b32 v172, v211 offset:2304
	ds_write_b32 v172, v212 offset:2560
	ds_write_b32 v172, v213 offset:2816
	ds_write_b32 v172, v214 offset:3072
	ds_write_b32 v172, v215 offset:3328
	ds_write_b32 v172, v216 offset:3584
	ds_write_b32 v172, v217 offset:3840
	ds_write_b32 v172, v218 offset:4096
	ds_write_b32 v172, v219 offset:4352
	ds_write_b32 v172, v220 offset:4608
	ds_write_b32 v172, v221 offset:4864
	ds_write_b32 v172, v222 offset:5120
	ds_write_b32 v172, v223 offset:5376
	ds_write_b32 v172, v224 offset:5632
	ds_write_b32 v172, v225 offset:5888
	ds_write_b32 v172, v226 offset:6144
	ds_write_b32 v172, v227 offset:6400
	ds_write_b32 v172, v228 offset:6656
	ds_write_b32 v172, v229 offset:6912
	ds_write_b32 v172, v230 offset:7168
	ds_write_b32 v172, v231 offset:7424
	ds_write_b32 v172, v232 offset:7680
	ds_write_b32 v172, v233 offset:7936
	ds_write_b32 v172, v234 offset:8192
	ds_write_b32 v172, v235 offset:8448
	ds_write_b32 v172, v236 offset:8704
	ds_write_b32 v172, v237 offset:8960
	ds_write_b32 v172, v238 offset:9216
	ds_write_b32 v172, v239 offset:9472
	ds_write_b32 v172, v240 offset:9728
	ds_write_b32 v172, v241 offset:9984
	ds_write_b32 v172, v242 offset:10240
	ds_write_b32 v172, v243 offset:10496
	ds_write_b32 v172, v244 offset:10752
	ds_write_b32 v172, v245 offset:11008
	ds_write_b32 v172, v246 offset:11264
	ds_write_b32 v172, v247 offset:11520
	ds_write_b32 v172, v248 offset:11776
	ds_write_b32 v172, v249 offset:12032
	s_waitcnt lgkmcnt(0)
	v_mul_u32_u24_e32 v1, 0xd0, v162
	v_lshlrev_b32_e32 v0, 4, v161
	v_add_u32_e32 v112, v1, v0
	v_lshlrev_b32_e32 v36, 6, v162
	v_sub_u32_e32 v176, v112, v36
	s_movk_i32 s13, 0x80
	s_cmp_lt_i32 s21, 1
	s_cselect_b32 s12, 0x2080, s13
	s_movk_i32 s13, 0x600
	v_add_u32_e32 v48, s12, v163
	v_mad_i64_i32 v[150:151], s[14:15], v48, s13, v[150:151]
	v_add_u32_e32 v48, s12, v164
	v_mad_i64_i32 v[154:155], s[14:15], v48, s13, v[154:155]
	s_lshl_b32 s12, s12, 1
	s_mov_b32 s13, 0
	v_lshl_add_u64 v[152:153], v[152:153], 0, s[12:13]
	s_mov_b32 s26, 0x18000
	s_mov_b32 s27, 0
	s_movk_i32 s30, 0x80
	s_mov_b32 s31, 0
	s_mov_b32 s14, 0xff800000
	s_mov_b32 s15, 0xff800000
	s_mov_b32 s28, 0
	v_mov_b32_e32 v0, 0
	v_mov_b32_e32 v1, 0
	v_mov_b32_e32 v2, 0
	v_mov_b32_e32 v3, 0
	v_mov_b32_e32 v4, 0
	v_mov_b32_e32 v5, 0
	v_mov_b32_e32 v6, 0
	v_mov_b32_e32 v7, 0
	v_mov_b32_e32 v8, 0
	v_mov_b32_e32 v9, 0
	v_mov_b32_e32 v10, 0
	v_mov_b32_e32 v11, 0
	v_mov_b32_e32 v12, 0
	v_mov_b32_e32 v13, 0
	v_mov_b32_e32 v14, 0
	v_mov_b32_e32 v15, 0
	v_mov_b32_e32 v16, 0
	v_mov_b32_e32 v17, 0
	v_mov_b32_e32 v18, 0
	v_mov_b32_e32 v19, 0
	v_mov_b32_e32 v20, 0
	v_mov_b32_e32 v21, 0
	v_mov_b32_e32 v22, 0
	v_mov_b32_e32 v23, 0
	v_mov_b32_e32 v24, 0
	v_mov_b32_e32 v25, 0
	v_mov_b32_e32 v26, 0
	v_mov_b32_e32 v27, 0
	v_mov_b32_e32 v28, 0
	v_mov_b32_e32 v29, 0
	v_mov_b32_e32 v30, 0
	v_mov_b32_e32 v31, 0
	v_mov_b32_e32 v32, 0
	v_mov_b32_e32 v33, 0
	v_mov_b32_e32 v34, 0
	v_mov_b32_e32 v35, 0
	v_mov_b32_e32 v36, 0
	v_mov_b32_e32 v37, 0
	v_mov_b32_e32 v38, 0
	v_mov_b32_e32 v39, 0
	v_mov_b32_e32 v40, 0
	v_mov_b32_e32 v41, 0
	v_mov_b32_e32 v42, 0
	v_mov_b32_e32 v43, 0
	v_mov_b32_e32 v44, 0
	v_mov_b32_e32 v45, 0
	v_mov_b32_e32 v46, 0
	v_mov_b32_e32 v47, 0
	v_mov_b32_e32 v156, 0
	v_mov_b32_e32 v157, 0
	v_readfirstlane_b32 s12, v170
	s_cmpk_ge_u32 s12, 0x100
	s_cbranch_scc1 .Lmla_B_entry
	.p2align	6

.Lmla_nowrite_B0:
	s_waitcnt lgkmcnt(9)
	v_mfma_f32_32x32x16_bf16 v[64:79], v[178:181], v[100:103], v[64:79]
	s_waitcnt lgkmcnt(8)
	v_mfma_f32_32x32x16_bf16 v[48:63], v[198:201], v[100:103], v[48:63]
	s_setprio 0
	s_waitcnt lgkmcnt(0)
	s_barrier
	s_mov_b32 s28, 1
	s_cmp_lt_i32 s28, s22
	s_cbranch_scc0 .Lmla_B_tail
	.p2align	6
